# GLA item staging de-serialised: lr + 32 v loads issued together, one wait, then pack + LDS writes
# speedup vs baseline: 1.0156x; 1.0022x over previous
.LBB0_501:
	s_ashr_i32 s28, s27, 2
	s_lshl_b32 s0, s28, 6
	s_ashr_i32 s1, s0, 31
	s_lshl_b64 s[20:21], s[0:1], 7
	v_lshl_add_u64 v[0:1], v[88:89], 0, s[20:21]
	global_load_dwordx4 v[240:243], v[0:1], off
	s_and_b32 s9, s27, 3
	s_mul_i32 s1, s28, 0x60000
	s_mul_hi_i32 s8, s0, 0x1800
	s_add_u32 s0, s90, s1
	s_addc_u32 s1, s91, s8
	s_lshl_b32 s8, s9, 8
	s_lshl_b32 s20, s9, 9
	s_add_u32 s20, s0, s20
	s_addc_u32 s21, s1, 0
	v_mov_b32_e32 v189, v91
	s_lshl_b32 s29, s9, 7
	s_movk_i32 s9, 0x1000
	s_add_u32 s0, s0, s8
	s_addc_u32 s1, s1, 0
	v_mov_b32_e32 v26, v204
	v_mov_b32_e32 v27, v91
	v_lshl_add_u64 v[0:1], s[20:21], 0, v[188:189]
	v_lshl_add_u64 v[2:3], v[0:1], 0, v[92:93]
	global_load_ushort v208, v[2:3], off offset:2048
	v_lshl_add_u64 v[2:3], v[0:1], 0, v[94:95]
	global_load_ushort v209, v[2:3], off offset:2048
	v_lshl_add_u64 v[2:3], v[0:1], 0, v[96:97]
	global_load_ushort v210, v[2:3], off offset:2048
	v_lshl_add_u64 v[2:3], v[0:1], 0, v[98:99]
	global_load_ushort v211, v[2:3], off offset:2048
	v_lshl_add_u64 v[2:3], v[0:1], 0, v[100:101]
	global_load_ushort v212, v[2:3], off offset:2048
	v_lshl_add_u64 v[2:3], v[0:1], 0, v[102:103]
	global_load_ushort v213, v[2:3], off offset:2048
	v_lshl_add_u64 v[2:3], v[0:1], 0, v[104:105]
	global_load_ushort v214, v[2:3], off offset:2048
	v_lshl_add_u64 v[2:3], v[0:1], 0, v[106:107]
	global_load_ushort v215, v[2:3], off offset:2048
	v_lshl_add_u64 v[2:3], v[0:1], 0, v[108:109]
	global_load_ushort v216, v[2:3], off offset:2048
	v_lshl_add_u64 v[2:3], v[0:1], 0, v[110:111]
	global_load_ushort v217, v[2:3], off offset:2048
	v_lshl_add_u64 v[2:3], v[0:1], 0, v[112:113]
	global_load_ushort v218, v[2:3], off offset:2048
	v_lshl_add_u64 v[2:3], v[0:1], 0, v[114:115]
	global_load_ushort v219, v[2:3], off offset:2048
	v_lshl_add_u64 v[2:3], v[0:1], 0, v[116:117]
	global_load_ushort v220, v[2:3], off offset:2048
	v_lshl_add_u64 v[2:3], v[0:1], 0, v[118:119]
	global_load_ushort v221, v[2:3], off offset:2048
	v_lshl_add_u64 v[2:3], v[0:1], 0, v[120:121]
	global_load_ushort v222, v[2:3], off offset:2048
	v_lshl_add_u64 v[2:3], v[0:1], 0, v[122:123]
	global_load_ushort v223, v[2:3], off offset:2048
	v_lshl_add_u64 v[2:3], v[0:1], 0, v[124:125]
	global_load_ushort v224, v[2:3], off offset:2048
	v_lshl_add_u64 v[2:3], v[0:1], 0, v[126:127]
	global_load_ushort v225, v[2:3], off offset:2048
	v_lshl_add_u64 v[2:3], v[0:1], 0, v[128:129]
	global_load_ushort v226, v[2:3], off offset:2048
	v_lshl_add_u64 v[2:3], v[0:1], 0, v[130:131]
	global_load_ushort v227, v[2:3], off offset:2048
	v_lshl_add_u64 v[2:3], v[0:1], 0, v[132:133]
	global_load_ushort v228, v[2:3], off offset:2048
	v_lshl_add_u64 v[2:3], v[0:1], 0, v[134:135]
	global_load_ushort v229, v[2:3], off offset:2048
	v_lshl_add_u64 v[2:3], v[0:1], 0, v[136:137]
	global_load_ushort v230, v[2:3], off offset:2048
	v_lshl_add_u64 v[2:3], v[0:1], 0, v[138:139]
	global_load_ushort v231, v[2:3], off offset:2048
	v_lshl_add_u64 v[2:3], v[0:1], 0, v[140:141]
	global_load_ushort v232, v[2:3], off offset:2048
	v_lshl_add_u64 v[2:3], v[0:1], 0, v[142:143]
	global_load_ushort v233, v[2:3], off offset:2048
	v_lshl_add_u64 v[2:3], v[0:1], 0, v[144:145]
	global_load_ushort v234, v[2:3], off offset:2048
	v_lshl_add_u64 v[2:3], v[0:1], 0, v[146:147]
	global_load_ushort v235, v[2:3], off offset:2048
	v_lshl_add_u64 v[2:3], v[0:1], 0, v[148:149]
	global_load_ushort v236, v[2:3], off offset:2048
	v_lshl_add_u64 v[2:3], v[0:1], 0, v[150:151]
	global_load_ushort v237, v[2:3], off offset:2048
	v_lshl_add_u64 v[2:3], v[0:1], 0, v[152:153]
	v_lshl_add_u64 v[0:1], v[0:1], 0, v[154:155]
	global_load_ushort v238, v[2:3], off offset:2048
	global_load_ushort v239, v[0:1], off offset:2048
	s_waitcnt vmcnt(0)
	ds_write_b128 v157, v[240:243]
	v_perm_b32 v208, v209, v208, s3
	v_perm_b32 v209, v211, v210, s3
	v_perm_b32 v210, v213, v212, s3
	v_perm_b32 v211, v215, v214, s3
	v_perm_b32 v212, v217, v216, s3
	v_perm_b32 v213, v219, v218, s3
	v_perm_b32 v214, v221, v220, s3
	v_perm_b32 v215, v223, v222, s3
	v_perm_b32 v216, v225, v224, s3
	v_perm_b32 v217, v227, v226, s3
	v_perm_b32 v218, v229, v228, s3
	v_perm_b32 v219, v231, v230, s3
	v_perm_b32 v220, v233, v232, s3
	v_perm_b32 v221, v235, v234, s3
	v_perm_b32 v222, v237, v236, s3
	v_perm_b32 v223, v239, v238, s3
	ds_write_b128 v192, v[208:211]
	ds_write_b128 v192, v[212:215] offset:16
	ds_write_b128 v192, v[216:219] offset:32
	ds_write_b128 v193, v[220:223]
	v_or_b32_e32 v0, s29, v156
	v_lshlrev_b32_e32 v90, 2, v0
	v_lshl_add_u64 v[16:17], v[158:159], 0, v[90:91]
	v_add_co_u32_e32 v6, vcc, s9, v16
	s_movk_i32 s9, 0x2000
	s_nop 0
	v_addc_co_u32_e32 v7, vcc, 0, v17, vcc
	v_add_co_u32_e32 v10, vcc, s9, v16
	s_movk_i32 s9, 0x3000
	s_nop 0
	v_addc_co_u32_e32 v11, vcc, 0, v17, vcc
	v_add_co_u32_e32 v14, vcc, s9, v16
	s_movk_i32 s9, 0x4000
	s_nop 0
	v_addc_co_u32_e32 v15, vcc, 0, v17, vcc
	v_add_co_u32_e32 v18, vcc, s9, v16
	s_movk_i32 s9, 0x5000
	s_nop 0
	v_addc_co_u32_e32 v19, vcc, 0, v17, vcc
	global_load_dword v0, v[16:17], off
	global_load_dword v2, v[16:17], off offset:2048
	global_load_dword v4, v[10:11], off offset:-4096
	s_nop 0
	global_load_dword v6, v[6:7], off offset:2048
	s_nop 0
	global_load_dword v8, v[10:11], off
	s_nop 0
	global_load_dword v10, v[10:11], off offset:2048
	s_nop 0
	global_load_dword v12, v[18:19], off offset:-4096
	s_nop 0
	global_load_dword v14, v[14:15], off offset:2048
	s_nop 0
	global_load_dword v1, v[18:19], off
	global_load_dword v3, v[18:19], off offset:2048
	v_add_co_u32_e32 v18, vcc, s9, v16
	s_movk_i32 s9, 0x6000
	s_nop 0
	v_addc_co_u32_e32 v19, vcc, 0, v17, vcc
	v_add_co_u32_e32 v20, vcc, s9, v16
	s_movk_i32 s9, 0x7000
	s_nop 0
	v_addc_co_u32_e32 v21, vcc, 0, v17, vcc
	v_add_co_u32_e32 v16, vcc, s9, v16
	global_load_dword v5, v[20:21], off offset:-4096
	global_load_dword v7, v[18:19], off offset:2048
	global_load_dword v9, v[20:21], off
	global_load_dword v11, v[20:21], off offset:2048
	v_addc_co_u32_e32 v17, vcc, 0, v17, vcc
	global_load_dword v13, v[16:17], off
	global_load_dword v15, v[16:17], off offset:2048
	v_lshl_add_u64 v[16:17], v[160:161], 0, v[90:91]
	v_lshlrev_b32_e32 v90, 1, v156
	global_load_dword v20, v[16:17], off
	v_lshl_add_u64 v[16:17], s[0:1], 0, v[90:91]
	v_lshl_add_u64 v[18:19], v[16:17], 0, v[162:163]
	global_load_ushort v21, v[18:19], off offset:1024
	v_lshl_add_u64 v[18:19], v[16:17], 0, v[164:165]
	global_load_ushort v36, v[18:19], off offset:1024
	v_lshl_add_u64 v[18:19], v[16:17], 0, v[166:167]
	global_load_ushort v22, v[18:19], off offset:1024
	v_lshl_add_u64 v[18:19], v[16:17], 0, v[168:169]
	global_load_ushort v37, v[18:19], off offset:1024
	v_lshl_add_u64 v[18:19], v[16:17], 0, v[170:171]
	global_load_ushort v34, v[18:19], off offset:1024
	v_lshl_add_u64 v[18:19], v[16:17], 0, v[172:173]
	global_load_ushort v23, v[18:19], off offset:1024
	v_lshl_add_u64 v[18:19], v[16:17], 0, v[174:175]
	global_load_ushort v35, v[18:19], off offset:1024
	v_lshl_add_u64 v[18:19], v[16:17], 0, v[176:177]
	global_load_ushort v18, v[18:19], off offset:1024
	s_mov_b32 s0, 8
	s_waitcnt lgkmcnt(0)
	s_barrier
	s_waitcnt vmcnt(8)
	v_mov_b32_e32 v90, v20
	s_waitcnt vmcnt(5)
	v_perm_b32 v33, v22, v21, s3
	s_waitcnt vmcnt(0)
	v_perm_b32 v28, v23, v18, s3

.LBB0_761:
	s_ashr_i32 s21, s43, 2
	s_lshl_b32 s24, s21, 6
	s_ashr_i32 s25, s24, 31
	s_lshl_b64 s[22:23], s[24:25], 7
	v_lshl_add_u64 v[0:1], v[56:57], 0, s[22:23]
	global_load_dwordx4 v[240:243], v[0:1], off
	s_and_b32 s11, s43, 3
	s_mul_i32 s0, s21, 0x60000
	s_mul_hi_i32 s10, s24, 0x1800
	s_add_u32 s0, s90, s0
	s_addc_u32 s10, s91, s10
	s_lshl_b32 s20, s11, 8
	s_lshl_b32 s22, s11, 9
	s_add_u32 s22, s0, s22
	s_addc_u32 s23, s10, 0
	v_mov_b32_e32 v157, v59
	v_mov_b32_e32 v17, v59
	v_lshl_add_u64 v[0:1], s[22:23], 0, v[156:157]
	v_lshl_add_u64 v[2:3], v[0:1], 0, v[60:61]
	global_load_ushort v208, v[2:3], off offset:2048
	v_lshl_add_u64 v[2:3], v[0:1], 0, v[62:63]
	global_load_ushort v209, v[2:3], off offset:2048
	v_lshl_add_u64 v[2:3], v[0:1], 0, v[64:65]
	global_load_ushort v210, v[2:3], off offset:2048
	v_lshl_add_u64 v[2:3], v[0:1], 0, v[66:67]
	global_load_ushort v211, v[2:3], off offset:2048
	v_lshl_add_u64 v[2:3], v[0:1], 0, v[68:69]
	global_load_ushort v212, v[2:3], off offset:2048
	v_lshl_add_u64 v[2:3], v[0:1], 0, v[70:71]
	global_load_ushort v213, v[2:3], off offset:2048
	v_lshl_add_u64 v[2:3], v[0:1], 0, v[72:73]
	global_load_ushort v214, v[2:3], off offset:2048
	v_lshl_add_u64 v[2:3], v[0:1], 0, v[74:75]
	global_load_ushort v215, v[2:3], off offset:2048
	s_lshl_b32 s22, s11, 7
	s_movk_i32 s11, 0x2000
	s_add_u32 s44, s0, s20
	s_addc_u32 s45, s10, 0
	v_lshl_add_u64 v[2:3], v[0:1], 0, v[76:77]
	global_load_ushort v216, v[2:3], off offset:2048
	v_lshl_add_u64 v[2:3], v[0:1], 0, v[78:79]
	global_load_ushort v217, v[2:3], off offset:2048
	v_lshl_add_u64 v[2:3], v[0:1], 0, v[80:81]
	global_load_ushort v218, v[2:3], off offset:2048
	v_lshl_add_u64 v[2:3], v[0:1], 0, v[82:83]
	global_load_ushort v219, v[2:3], off offset:2048
	v_lshl_add_u64 v[2:3], v[0:1], 0, v[84:85]
	global_load_ushort v220, v[2:3], off offset:2048
	v_lshl_add_u64 v[2:3], v[0:1], 0, v[86:87]
	global_load_ushort v221, v[2:3], off offset:2048
	v_lshl_add_u64 v[2:3], v[0:1], 0, v[88:89]
	global_load_ushort v222, v[2:3], off offset:2048
	v_lshl_add_u64 v[2:3], v[0:1], 0, v[90:91]
	global_load_ushort v223, v[2:3], off offset:2048
	v_lshl_add_u64 v[2:3], v[0:1], 0, v[92:93]
	global_load_ushort v224, v[2:3], off offset:2048
	v_lshl_add_u64 v[2:3], v[0:1], 0, v[94:95]
	global_load_ushort v225, v[2:3], off offset:2048
	v_lshl_add_u64 v[2:3], v[0:1], 0, v[96:97]
	global_load_ushort v226, v[2:3], off offset:2048
	v_lshl_add_u64 v[2:3], v[0:1], 0, v[98:99]
	global_load_ushort v227, v[2:3], off offset:2048
	v_lshl_add_u64 v[2:3], v[0:1], 0, v[100:101]
	global_load_ushort v228, v[2:3], off offset:2048
	v_lshl_add_u64 v[2:3], v[0:1], 0, v[102:103]
	global_load_ushort v229, v[2:3], off offset:2048
	v_lshl_add_u64 v[2:3], v[0:1], 0, v[104:105]
	global_load_ushort v230, v[2:3], off offset:2048
	v_lshl_add_u64 v[2:3], v[0:1], 0, v[106:107]
	global_load_ushort v231, v[2:3], off offset:2048
	v_lshl_add_u64 v[2:3], v[0:1], 0, v[108:109]
	global_load_ushort v232, v[2:3], off offset:2048
	v_lshl_add_u64 v[2:3], v[0:1], 0, v[110:111]
	global_load_ushort v233, v[2:3], off offset:2048
	v_lshl_add_u64 v[2:3], v[0:1], 0, v[112:113]
	global_load_ushort v234, v[2:3], off offset:2048
	v_lshl_add_u64 v[2:3], v[0:1], 0, v[114:115]
	global_load_ushort v235, v[2:3], off offset:2048
	v_lshl_add_u64 v[2:3], v[0:1], 0, v[116:117]
	global_load_ushort v236, v[2:3], off offset:2048
	v_lshl_add_u64 v[2:3], v[0:1], 0, v[118:119]
	global_load_ushort v237, v[2:3], off offset:2048
	v_lshl_add_u64 v[2:3], v[0:1], 0, v[120:121]
	v_lshl_add_u64 v[0:1], v[0:1], 0, v[122:123]
	global_load_ushort v238, v[2:3], off offset:2048
	global_load_ushort v239, v[0:1], off offset:2048
	s_waitcnt vmcnt(0)
	ds_write_b128 v125, v[240:243]
	v_perm_b32 v208, v209, v208, s30
	v_perm_b32 v209, v211, v210, s30
	v_perm_b32 v210, v213, v212, s30
	v_perm_b32 v211, v215, v214, s30
	v_perm_b32 v212, v217, v216, s30
	v_perm_b32 v213, v219, v218, s30
	v_perm_b32 v214, v221, v220, s30
	v_perm_b32 v215, v223, v222, s30
	v_perm_b32 v216, v225, v224, s30
	v_perm_b32 v217, v227, v226, s30
	v_perm_b32 v218, v229, v228, s30
	v_perm_b32 v219, v231, v230, s30
	v_perm_b32 v220, v233, v232, s30
	v_perm_b32 v221, v235, v234, s30
	v_perm_b32 v222, v237, v236, s30
	v_perm_b32 v223, v239, v238, s30
	ds_write_b128 v160, v[208:211]
	ds_write_b128 v160, v[212:215] offset:16
	ds_write_b128 v160, v[216:219] offset:32
	ds_write_b128 v161, v[220:223]
	v_or_b32_e32 v0, s22, v124
	v_lshlrev_b32_e32 v16, 2, v0
	v_lshl_add_u64 v[18:19], v[126:127], 0, v[16:17]
	v_add_co_u32_e32 v6, vcc, s31, v18
	global_load_dword v0, v[18:19], off
	global_load_dword v2, v[18:19], off offset:2048
	v_addc_co_u32_e32 v7, vcc, 0, v19, vcc
	v_add_co_u32_e32 v10, vcc, s11, v18
	s_movk_i32 s11, 0x3000
	s_nop 0
	v_addc_co_u32_e32 v11, vcc, 0, v19, vcc
	v_add_co_u32_e32 v14, vcc, s11, v18
	s_movk_i32 s11, 0x4000
	s_nop 0
	v_addc_co_u32_e32 v15, vcc, 0, v19, vcc
	v_add_co_u32_e32 v20, vcc, s11, v18
	s_movk_i32 s11, 0x5000
	s_nop 0
	v_addc_co_u32_e32 v21, vcc, 0, v19, vcc
	global_load_dword v4, v[10:11], off offset:-4096
	s_nop 0
	global_load_dword v6, v[6:7], off offset:2048
	s_nop 0
	global_load_dword v8, v[10:11], off
	s_nop 0
	global_load_dword v10, v[10:11], off offset:2048
	s_nop 0
	global_load_dword v12, v[20:21], off offset:-4096
	s_nop 0
	global_load_dword v14, v[14:15], off offset:2048
	s_nop 0
	global_load_dword v1, v[20:21], off
	global_load_dword v3, v[20:21], off offset:2048
	v_add_co_u32_e32 v20, vcc, s11, v18
	s_movk_i32 s11, 0x6000
	s_nop 0
	v_addc_co_u32_e32 v21, vcc, 0, v19, vcc
	v_add_co_u32_e32 v22, vcc, s11, v18
	s_movk_i32 s11, 0x7000
	s_nop 0
	v_addc_co_u32_e32 v23, vcc, 0, v19, vcc
	v_add_co_u32_e32 v18, vcc, s11, v18
	global_load_dword v5, v[22:23], off offset:-4096
	global_load_dword v7, v[20:21], off offset:2048
	global_load_dword v9, v[22:23], off
	global_load_dword v11, v[22:23], off offset:2048
	v_addc_co_u32_e32 v19, vcc, 0, v19, vcc
	global_load_dword v13, v[18:19], off
	global_load_dword v15, v[18:19], off offset:2048
	v_lshlrev_b32_e32 v18, 1, v124
	v_mov_b32_e32 v19, v59
	v_lshl_add_u64 v[18:19], s[44:45], 0, v[18:19]
	v_lshl_add_u64 v[16:17], v[128:129], 0, v[16:17]
	v_lshl_add_u64 v[20:21], v[18:19], 0, v[130:131]
	global_load_dword v16, v[16:17], off
	s_nop 0
	global_load_ushort v36, v[20:21], off
	global_load_ushort v37, v[20:21], off offset:1024
	v_lshl_add_u64 v[20:21], v[18:19], 0, v[132:133]
	global_load_ushort v34, v[20:21], off
	global_load_ushort v35, v[20:21], off offset:1024
	v_lshl_add_u64 v[20:21], v[18:19], 0, v[134:135]
	global_load_ushort v32, v[20:21], off
	global_load_ushort v33, v[20:21], off offset:1024
	v_lshl_add_u64 v[20:21], v[18:19], 0, v[136:137]
	global_load_ushort v30, v[20:21], off
	global_load_ushort v31, v[20:21], off offset:1024
	v_lshl_add_u64 v[20:21], v[18:19], 0, v[138:139]
	global_load_ushort v28, v[20:21], off
	global_load_ushort v29, v[20:21], off offset:1024
	v_lshl_add_u64 v[20:21], v[18:19], 0, v[140:141]
	global_load_ushort v26, v[20:21], off
	global_load_ushort v27, v[20:21], off offset:1024
	v_lshl_add_u64 v[20:21], v[18:19], 0, v[142:143]
	global_load_ushort v24, v[20:21], off
	global_load_ushort v25, v[20:21], off offset:1024
	v_lshl_add_u64 v[20:21], v[18:19], 0, v[144:145]
	global_load_ushort v22, v[20:21], off
	global_load_ushort v23, v[20:21], off offset:1024
	v_mov_b32_e32 v20, v59
	s_and_saveexec_b64 s[10:11], s[6:7]
	s_cbranch_execz .LBB0_763
	v_add_u32_e32 v20, s21, v162
	v_ashrrev_i32_e32 v21, 31, v20
	v_lshlrev_b64 v[20:21], 11, v[20:21]
	v_lshl_add_u64 v[20:21], s[74:75], 0, v[20:21]
	s_lshl_b32 s0, s22, 2
	v_lshl_add_u64 v[20:21], v[20:21], 0, s[0:1]
	v_lshlrev_b32_e32 v38, 2, v124
	v_mov_b32_e32 v39, v59
	v_lshl_add_u64 v[20:21], v[20:21], 0, v[38:39]
	global_load_dword v20, v[20:21], off
